# P0: quantise x rows first and run the column-absmax passes last, so W_ffn1_in is re-read for quantisation right after its absmax pass
# speedup vs baseline: 1.0015x; 1.0015x over previous
; __global__ void __launch_bounds__(512, 2) mk_fwd(Args args) {
;     ...
;         for (int m0 = gw; m0 < M; m0 += 2 * NGW) {
;             f32x4 v[2][8]; int mm[2];
; #pragma unroll
;             for (int rr = 0; rr < 2; ++rr) { mm[rr] = (m0 + rr * NGW < M) ? m0 + rr * NGW : m0;
;                 const float* xr = (mm[rr] < MP) ? x_prompt + (size_t)mm[rr] * DM : x_sample + (size_t)(mm[rr] - MP) * DM;
;                 const f32x4* x4 = (const f32x4*)xr + lane;
; #pragma unroll
;                 for (int j = 0; j < 8; ++j) v[rr][j] = x4[64 * j]; }
; #pragma unroll
;             for (int rr = 0; rr < 2; ++rr) {
;                 float s = 0.f, mx = 0.f;
; #pragma unroll
;                 for (int j = 0; j < 8; ++j) { s += (v[rr][j][0] * v[rr][j][0] + v[rr][j][1] * v[rr][j][1]) + (v[rr][j][2] * v[rr][j][2] + v[rr][j][3] * v[rr][j][3]);
;                     mx = fmaxf(mx, fmaxf(fmaxf(fabsf(v[rr][j][0]), fabsf(v[rr][j][1])), fmaxf(fabsf(v[rr][j][2]), fabsf(v[rr][j][3])))); }
;                 s = wave_sum(s);
; #pragma unroll
;                 for (int o = 1; o < 64; o <<= 1) mx = fmaxf(mx, __shfl_xor(mx, o));
;                 const float sc = mx > 0.f ? 127.f / mx : 0.f;
;                 unsigned* o4 = (unsigned*)((unsigned char*)HB + (size_t)mm[rr] * DM) + lane;
; #pragma unroll
;                 for (int j = 0; j < 8; ++j) { unsigned w = 0u;
; #pragma unroll
;                     for (int e = 0; e < 4; ++e) w |= ((unsigned)(int)rintf(v[rr][j][e] * sc) & 0xffu) << (8 * e);
;                     o4[64 * j] = w; }
;                 if (lane == 0) frow1[mm[rr]] = __builtin_amdgcn_rsqf(s * (1.f / 2048.f) + EPS) * mx * (1.f / 127.f);
;             }
;         }
.LBB0_5:
	s_or_b64 exec, exec, s[2:3]
	s_lshr_b32 s52, s6, 6
	s_lshl_b32 s2, s61, 3
	s_add_i32 s96, s52, s2
	s_lshl_b32 s63, s54, 3
	s_add_u32 s6, s74, 0x4b600
	s_addc_u32 s7, s75, 0
	s_add_u32 s2, s74, 0x100000
	s_addc_u32 s3, s75, 0
	v_writelane_b32 v239, s2, 23
	v_and_b32_e32 v176, 63, v177
	s_nop 0
	v_writelane_b32 v239, s3, 24
	s_add_u32 s2, s74, 0x7380000
	s_addc_u32 s3, s75, 0
	v_writelane_b32 v239, s2, 25
	s_cmp_lt_i32 s56, 1
	s_nop 0
	v_writelane_b32 v239, s3, 26
	s_cselect_b64 s[2:3], -1, 0
	s_cmp_gt_i32 s57, 0
	s_cselect_b64 s[4:5], -1, 0
	s_and_b64 s[2:3], s[2:3], s[4:5]
	s_andn2_b64 vcc, exec, s[2:3]
	s_cbranch_vccnz .LBB0_95
	s_cmpk_gt_i32 s96, 0x5fff
	s_cbranch_scc1 .Lxq_done
	v_mbcnt_lo_u32_b32 v1, -1, 0
	v_mbcnt_hi_u32_b32 v2, -1, v1
	v_and_b32_e32 v1, 64, v2
	v_add_u32_e32 v3, 64, v1
	v_xor_b32_e32 v1, 1, v2
	v_cmp_lt_i32_e32 vcc, v1, v3
	v_xor_b32_e32 v4, 2, v2
	v_readlane_b32 s4, v239, 25
	v_cndmask_b32_e32 v1, v2, v1, vcc
	v_cmp_lt_i32_e32 vcc, v4, v3
	s_waitcnt lgkmcnt(0)
	s_add_u32 s16, s74, 0xab000
	v_mov_b32_e32 v67, 0
	v_cndmask_b32_e32 v4, v2, v4, vcc
	v_lshlrev_b32_e32 v70, 2, v4
	v_xor_b32_e32 v4, 4, v2
	v_cmp_lt_i32_e32 vcc, v4, v3
	v_lshlrev_b32_e32 v66, 2, v176
	v_readlane_b32 s5, v239, 26
	v_cndmask_b32_e32 v4, v2, v4, vcc
	v_lshlrev_b32_e32 v71, 2, v4
	v_xor_b32_e32 v4, 8, v2
	v_cmp_lt_i32_e32 vcc, v4, v3
	s_addc_u32 s17, s75, 0
	v_lshlrev_b32_e32 v1, 2, v1
	v_cndmask_b32_e32 v4, v2, v4, vcc
	v_lshlrev_b32_e32 v72, 2, v4
	v_xor_b32_e32 v4, 16, v2
	v_cmp_lt_i32_e32 vcc, v4, v3
	v_lshl_add_u64 v[68:69], s[4:5], 0, v[66:67]
	v_cmp_eq_u32_e64 s[4:5], 0, v176
	v_cndmask_b32_e32 v4, v2, v4, vcc
	v_lshlrev_b32_e32 v73, 2, v4
	v_xor_b32_e32 v4, 32, v2
	v_cmp_lt_i32_e32 vcc, v4, v3
	s_lshl_b32 s18, s54, 4
	v_lshlrev_b32_e32 v66, 4, v176
	v_cndmask_b32_e32 v2, v2, v4, vcc
	v_lshlrev_b32_e32 v74, 2, v2
	s_movk_i32 s19, 0x1000
	s_mov_b32 s20, 0x42fe0000
	s_mov_b32 s21, 0xc0c0500
	s_mov_b32 s22, 0xff0000
	v_mov_b32_e32 v75, 0x358637bd
	s_mov_b32 s10, s96
	s_branch .LBB0_15

; __global__ void __launch_bounds__(512, 2) mk_fwd(Args args) {
;     ...
;         {
;             const float* Win = args.in[6]; const float* gm = args.in[5];
;             for (int t = bx * 512 + tid; t < 64 * NIN; t += 2 * G * 512) {
;                 const int tB = (t + G * 512 < 64 * NIN) ? t + G * 512 : t;
;                 const int ch = t / NIN, n = t - ch * NIN, chB = tB / NIN, nB = tB - chB * NIN; float a[32], b[32];
; #pragma unroll
;                 for (int k = 0; k < 32; ++k) { a[k] = Win[(size_t)(ch * 32 + k) * NIN + n]; b[k] = Win[(size_t)(chB * 32 + k) * NIN + nB]; }
;                 float mx = 0.f, mxB = 0.f;
; #pragma unroll
;                 for (int k = 0; k < 32; ++k) { mx = fmaxf(mx, fabsf(a[k] * gm[ch * 32 + k])); mxB = fmaxf(mxB, fabsf(b[k] * gm[chB * 32 + k])); }
;                 atomicMax((int*)colmax + n, __float_as_int(mx)); atomicMax((int*)colmax + nB, __float_as_int(mxB));
;             }
;         }
.Lxq_done:
	v_lshl_add_u32 v1, s61, 9, v177
	s_mov_b32 s10, 0x88000
	v_cmp_gt_i32_e32 vcc, s10, v1
	s_and_saveexec_b64 s[4:5], vcc
	s_load_dwordx16 s[12:27], s[0:1], 0x0
	s_cbranch_execz .LBB0_9
	s_lshl_b32 s11, s54, 9
	s_waitcnt lgkmcnt(0)
	s_lshl_b32 s12, s54, 10
	s_mov_b64 s[8:9], 0
	s_mov_b32 s13, 0x78787879
	s_movk_i32 s14, 0xde00
	s_mov_b32 s15, 0x87fff
	v_mov_b32_e32 v38, v1

; __device__ __forceinline__ unsigned xb_ld(unsigned* p)              { return __hip_atomic_load(p, __ATOMIC_RELAXED, __HIP_MEMORY_SCOPE_AGENT); }
; __device__ __forceinline__ void xcd_barrier_complete(unsigned* bar, unsigned x, unsigned& nloc, unsigned& nx) {
;     const unsigned G = gridDim.x * gridDim.y * gridDim.z;
;     unsigned sum, cnt, mine, sp = 0u;
;     for (;;) {
;         sum = 0u; cnt = 0u; mine = 0u;
; #pragma unroll
;         for (unsigned j = 0; j < 16; ++j) { const unsigned c = xb_ld(&bar[XB_XCNT(j)]); sum += c; cnt += (c > 0u) ? 1u : 0u; mine = (j == x) ? c : mine; }
; __device__ __forceinline__ void xcd_barrier(const XcdBarrier& b) {
;     asm volatile("s_waitcnt vmcnt(0)" ::: "memory");
;     __syncthreads();
;     if (threadIdx.x == 0) {
;         unsigned* bar = b.bar;
;         __builtin_amdgcn_s_waitcnt(0);
;         unsigned nloc = b.st[0], nx = b.st[1];
;         if (nloc == 0u) { xcd_barrier_complete(bar, b.x, nloc, nx); b.st[0] = nloc; b.st[1] = nx; }
.LBB0_12:
	s_or_b64 exec, exec, s[4:5]
.LBB0_19:
	s_waitcnt vmcnt(0)
	s_waitcnt lgkmcnt(0)
	s_barrier
	s_mov_b64 s[4:5], exec
	v_readlane_b32 s10, v239, 21
	v_readlane_b32 s11, v239, 22
	s_and_b64 s[10:11], s[4:5], s[10:11]
	s_mov_b64 exec, s[10:11]
	s_cbranch_execz .LBB0_71
	s_add_i32 s10, 0, 0x22400
	v_mov_b32_e32 v1, s10
	s_waitcnt vmcnt(0) expcnt(0) lgkmcnt(0)
	ds_read_b32 v3, v1
	s_add_i32 s10, 0, 0x22404
	v_mov_b32_e32 v1, s10
	ds_read_b32 v1, v1
	s_waitcnt lgkmcnt(1)
	v_cmp_ne_u32_e32 vcc, 0, v3
	s_cbranch_vccnz .LBB0_35
	v_readlane_b32 s10, v239, 0
	v_readlane_b32 s11, v239, 1
	s_load_dwordx2 s[14:15], s[10:11], 0x4
	s_add_u32 s10, s74, 0x48200
	s_addc_u32 s11, s75, 0
	s_add_u32 s12, s74, 0x48400
	s_addc_u32 s13, s75, 0
	s_waitcnt lgkmcnt(0)
	s_mul_i32 s33, s14, s54
	s_add_u32 s14, s74, 0x48500
	s_mul_i32 s33, s33, s15
	s_addc_u32 s15, s75, 0
	s_add_u32 s16, s74, 0x48600
	s_addc_u32 s17, s75, 0
	s_add_u32 s18, s74, 0x48700
	s_addc_u32 s19, s75, 0
	s_add_u32 s20, s74, 0x48800
	s_addc_u32 s21, s75, 0
	s_add_u32 s22, s74, 0x48900
	s_addc_u32 s23, s75, 0
	s_add_u32 s24, s74, 0x48a00
	s_addc_u32 s25, s75, 0
	s_add_u32 s26, s74, 0x48b00
	s_addc_u32 s27, s75, 0
	s_add_u32 s28, s74, 0x48c00
	s_addc_u32 s29, s75, 0
	s_add_u32 s30, s74, 0x48d00
	s_addc_u32 s31, s75, 0
	s_add_u32 s34, s74, 0x48e00
	s_addc_u32 s35, s75, 0
	s_add_u32 s36, s74, 0x48f00
	s_addc_u32 s37, s75, 0
	s_add_u32 s38, s74, 0x49000
	s_addc_u32 s39, s75, 0
	s_add_u32 s40, s74, 0x49100
	s_addc_u32 s41, s75, 0
	s_add_u32 s42, s74, 0x49200
	s_addc_u32 s43, s75, 0
	s_add_u32 s44, s74, 0x49300
	s_addc_u32 s45, s75, 0
	s_mov_b32 s53, 1
	v_mov_b32_e32 v17, 0
	s_branch .LBB0_23
